# SSD states: a_log load hoisted next to the dt loads (on top of v20)
# speedup vs baseline: 1.0032x; 1.0032x over previous
; __device__ __forceinline__ unsigned cvtpk(float lo, float hi) { f32x2_t v = {lo, hi}; bf16x2_t b = __builtin_convertvector(v, bf16x2_t); return __builtin_bit_cast(unsigned, b); }
; __device__ __forceinline__ float lo16(unsigned u) { return __uint_as_float(u << 16); }
; __device__ __forceinline__ float hi16(unsigned u) { return __uint_as_float(u & 0xffff0000u); }
; __device__ __forceinline__ float silu_fast(float v) { return v * __builtin_amdgcn_rcpf(1.f + __builtin_amdgcn_exp2f(-v * LOG2E)); }
; template <int NR, class Put>
; __device__ __forceinline__ void conv_compute_n(const ConvRawN<NR>& R, const float* cw, const float* cb, int col0, int rg, const Put& put) {
;     const f32x4 w0a = *(const f32x4*)(cw + col0), w0b = *(const f32x4*)(cw + col0 + 4), w1a = *(const f32x4*)(cw + XBCW + col0), w1b = *(const f32x4*)(cw + XBCW + col0 + 4);
;     const f32x4 w2a = *(const f32x4*)(cw + 2 * XBCW + col0), w2b = *(const f32x4*)(cw + 2 * XBCW + col0 + 4), ba = *(const f32x4*)(cb + col0), bb = *(const f32x4*)(cb + col0 + 4);
;     const int r0 = NR * rg;
; #pragma unroll
;     for (int rr = 0; rr < NR; ++rr) {
;         const u32x4 xm = R.r[rr], x0 = R.r[rr + 1], xp = R.r[rr + 2]; u32x4 o;
; #pragma unroll
;         for (int e = 0; e < 4; ++e) {
;             const float wl0 = e < 2 ? w0a[2 * e] : w0b[2 * e - 4], wh0 = e < 2 ? w0a[2 * e + 1] : w0b[2 * e - 3];
;             const float wl1 = e < 2 ? w1a[2 * e] : w1b[2 * e - 4], wh1 = e < 2 ? w1a[2 * e + 1] : w1b[2 * e - 3];
;             const float wl2 = e < 2 ? w2a[2 * e] : w2b[2 * e - 4], wh2 = e < 2 ? w2a[2 * e + 1] : w2b[2 * e - 3];
;             const float bl = e < 2 ? ba[2 * e] : bb[2 * e - 4], bh = e < 2 ? ba[2 * e + 1] : bb[2 * e - 3];
;             const float vl = bl + wl0 * lo16(xm[e]) + wl1 * lo16(x0[e]) + wl2 * lo16(xp[e]);
;             const float vh = bh + wh0 * hi16(xm[e]) + wh1 * hi16(x0[e]) + wh2 * hi16(xp[e]);
;             o[e] = cvtpk(silu_fast(vl), silu_fast(vh));
;         }
;         put(r0 + rr, o);
; __device__ __forceinline__ void states_unit(Frame& F, const Ptrs& P, int b, int c, int g, int hh) {
;     ...
;         __syncthreads();
;         float dv0, dv1; vec_load(F, P, b, c, h0, dv0, dv1);
;         conv_compute_n<4>(Rb, P.conv_w, P.conv_b, 1024 + g * 128 + 8 * chb, rgb, PutTr{lds + L_BIMG, chb});
;         vec_compute(F, P, b, c, h0, dv0, dv1, DEC);
.LBB0_571:
	s_or_b64 exec, exec, s[0:1]
	v_lshlrev_b32_e32 v56, 2, v56
	s_barrier
	v_mbcnt_lo_u32_b32 v106, -1, 0
	v_mbcnt_hi_u32_b32 v106, -1, v106
	global_load_dwordx4 v[72:75], v56, s[24:25]
	global_load_dwordx4 v[76:79], v56, s[26:27]
	global_load_dwordx4 v[60:63], v56, s[24:25] offset:16
	global_load_dwordx4 v[64:67], v56, s[26:27] offset:16
	global_load_dwordx4 v[80:83], v56, s[22:23]
	global_load_dwordx4 v[68:71], v56, s[22:23] offset:16
	global_load_dwordx4 v[84:87], v56, s[28:29]
	s_nop 0
	global_load_dwordx4 v[56:59], v56, s[28:29] offset:16
	v_or_b32_e32 v105, s84, v99
	s_cmp_eq_u32 s84, 63
	v_lshlrev_b32_e32 v114, 1, v98
	v_lshlrev_b32_e32 v117, 4, v98
	v_cmp_ne_u32_e64 s[0:1], 0, v105
	s_cselect_b64 s[72:73], -1, 0
	s_or_b32 s4, s4, s85
	v_ashrrev_i32_e32 v107, 31, v106
	s_waitcnt vmcnt(22)
	v_lshlrev_b32_e32 v112, 16, v50
	v_and_b32_e32 v113, 0xffff0000, v50
	v_cndmask_b32_e64 v105, 0, v91, s[0:1]
	v_and_b32_e32 v50, 24, v114
	v_and_b32_e32 v114, 48, v117
	v_cndmask_b32_e64 v117, 0, v89, s[0:1]
	v_cndmask_b32_e64 v91, 0, v88, s[0:1]
	v_lshl_add_u64 v[88:89], s[4:5], 0, v[106:107]
	s_add_i32 s16, s16, s35
	v_lshlrev_b64 v[88:89], 7, v[88:89]
	s_mov_b32 s3, s17
	v_lshrrev_b32_e32 v115, 6, v100
	s_lshl_b32 s2, s16, 2
	v_lshl_add_u64 v[88:89], s[20:21], 0, v[88:89]
	v_cmp_eq_u32_e32 vcc, 31, v99
	v_lshlrev_b32_e32 v116, 8, v99
	v_add_u32_e32 v50, v50, v115
	v_lshl_add_u64 v[88:89], v[88:89], 0, s[2:3]
	v_lshlrev_b32_e32 v108, 16, v48
	v_and_b32_e32 v109, 0xffff0000, v48
	s_waitcnt vmcnt(21)
	v_lshlrev_b32_e32 v98, 16, v52
	v_and_b32_e32 v99, 0xffff0000, v52
	v_lshlrev_b32_e32 v110, 16, v49
	v_and_b32_e32 v111, 0xffff0000, v49
	v_lshlrev_b32_e32 v48, 16, v53
	v_and_b32_e32 v49, 0xffff0000, v53
	v_lshlrev_b32_e32 v52, 16, v54
	v_and_b32_e32 v53, 0xffff0000, v54
	v_and_b32_e32 v54, 0x300, v116
	v_cndmask_b32_e64 v116, 0, v90, s[0:1]
	s_and_b64 s[0:1], s[72:73], vcc
	v_lshl_add_u32 v50, v50, 10, 0
	v_lshlrev_b32_e32 v90, 16, v91
	v_and_b32_e32 v91, 0xffff0000, v91
	v_add_co_u32_e32 v106, vcc, s65, v88
	v_add3_u32 v124, v50, v54, v114
	s_nop 0
	v_addc_co_u32_e32 v107, vcc, 0, v89, vcc
	v_mov_b32_e32 v141, s2
	global_load_dword v141, v141, s[68:69]
	global_load_dword v50, v[88:89], off
	global_load_dword v54, v[106:107], off
	s_waitcnt vmcnt(20)
	v_cndmask_b32_e64 v120, v95, 0, s[0:1]
	v_cndmask_b32_e64 v121, v94, 0, s[0:1]
	v_cndmask_b32_e64 v122, v93, 0, s[0:1]
	v_cndmask_b32_e64 v123, v92, 0, s[0:1]
	v_lshlrev_b32_e32 v92, 16, v117
	v_and_b32_e32 v93, 0xffff0000, v117
	v_lshlrev_b32_e32 v94, 16, v116
	v_and_b32_e32 v95, 0xffff0000, v116
	v_lshlrev_b32_e32 v116, 16, v44
	v_and_b32_e32 v117, 0xffff0000, v44
	s_waitcnt vmcnt(8)
	v_pk_fma_f32 v[88:89], v[72:73], v[90:91], v[76:77]
	v_pk_fma_f32 v[90:91], v[74:75], v[92:93], v[78:79]
	s_waitcnt vmcnt(6)
	v_pk_fma_f32 v[92:93], v[60:61], v[94:95], v[64:65]
	s_waitcnt vmcnt(5)
	v_pk_fma_f32 v[88:89], v[80:81], v[108:109], v[88:89]
	v_pk_fma_f32 v[90:91], v[82:83], v[110:111], v[90:91]
	s_waitcnt vmcnt(3)
	v_pk_fma_f32 v[88:89], v[84:85], v[98:99], v[88:89]
	v_pk_fma_f32 v[92:93], v[68:69], v[112:113], v[92:93]
	v_mul_f32_e32 v94, 0xbfb8aa3b, v88
	v_mul_f32_e32 v95, 0xbfb8aa3b, v89
	v_exp_f32_e32 v94, v94
	v_exp_f32_e32 v95, v95
	v_pk_fma_f32 v[90:91], v[86:87], v[48:49], v[90:91]
	s_waitcnt vmcnt(2)
	v_pk_fma_f32 v[92:93], v[56:57], v[52:53], v[92:93]
	v_add_f32_e32 v94, 1.0, v94
	v_add_f32_e32 v95, 1.0, v95
	v_rcp_f32_e32 v94, v94
	v_rcp_f32_e32 v95, v95
	v_mul_f32_e32 v106, 0xbfb8aa3b, v90
	v_mul_f32_e32 v107, 0xbfb8aa3b, v91
	v_exp_f32_e32 v106, v106
	v_exp_f32_e32 v107, v107
	v_pk_mul_f32 v[88:89], v[88:89], v[94:95]
	v_mul_f32_e32 v94, 0xbfb8aa3b, v92
	v_mul_f32_e32 v95, 0xbfb8aa3b, v93
	v_exp_f32_e32 v94, v94
	v_exp_f32_e32 v95, v95
	v_add_f32_e32 v106, 1.0, v106
	v_add_f32_e32 v107, 1.0, v107
	v_rcp_f32_e32 v106, v106
	v_rcp_f32_e32 v107, v107
	v_add_f32_e32 v94, 1.0, v94
	v_add_f32_e32 v95, 1.0, v95
	v_rcp_f32_e32 v94, v94
	v_rcp_f32_e32 v95, v95
	v_pk_mul_f32 v[90:91], v[90:91], v[106:107]
	v_cvt_pk_bf16_f32 v88, v88, v89
	v_cvt_pk_bf16_f32 v89, v90, v91
	v_pk_mul_f32 v[90:91], v[92:93], v[94:95]
	v_lshlrev_b32_e32 v92, 16, v105
	v_and_b32_e32 v93, 0xffff0000, v105
	v_pk_fma_f32 v[92:93], v[62:63], v[92:93], v[66:67]
	v_lshlrev_b32_e32 v94, 16, v51
	v_and_b32_e32 v95, 0xffff0000, v51
	v_pk_fma_f32 v[92:93], v[70:71], v[94:95], v[92:93]
	v_lshlrev_b32_e32 v106, 16, v55
	v_and_b32_e32 v107, 0xffff0000, v55
	v_pk_fma_f32 v[92:93], v[58:59], v[106:107], v[92:93]
	v_pk_fma_f32 v[108:109], v[72:73], v[108:109], v[76:77]
	v_mul_f32_e32 v51, 0xbfb8aa3b, v92
	v_exp_f32_e32 v51, v51
	v_mul_f32_e32 v55, 0xbfb8aa3b, v93
	v_exp_f32_e32 v55, v55
	v_pk_fma_f32 v[108:109], v[80:81], v[98:99], v[108:109]
	v_add_f32_e32 v51, 1.0, v51
	v_rcp_f32_e32 v114, v51
	v_add_f32_e32 v51, 1.0, v55
	v_rcp_f32_e32 v115, v51
	v_pk_fma_f32 v[108:109], v[84:85], v[116:117], v[108:109]
	v_cvt_pk_bf16_f32 v90, v90, v91
	v_mul_f32_e32 v44, 0xbfb8aa3b, v108
	v_exp_f32_e32 v44, v44
	v_mul_f32_e32 v55, 0xbfb8aa3b, v109
	v_exp_f32_e32 v55, v55
	v_pk_mul_f32 v[92:93], v[92:93], v[114:115]
	v_add_f32_e32 v44, 1.0, v44
	v_cvt_pk_bf16_f32 v91, v92, v93
	ds_write_b128 v124, v[88:91]
	v_pk_fma_f32 v[90:91], v[74:75], v[110:111], v[78:79]
	v_lshlrev_b32_e32 v92, 16, v45
	v_pk_fma_f32 v[90:91], v[82:83], v[48:49], v[90:91]
	v_and_b32_e32 v93, 0xffff0000, v45
	v_rcp_f32_e32 v118, v44
	v_add_f32_e32 v44, 1.0, v55
	v_pk_fma_f32 v[90:91], v[86:87], v[92:93], v[90:91]
	v_rcp_f32_e32 v119, v44
	v_mul_f32_e32 v44, 0xbfb8aa3b, v90
	v_exp_f32_e32 v45, v44
	v_mul_f32_e32 v44, 0xbfb8aa3b, v91
	v_exp_f32_e32 v51, v44
;     __device__ __forceinline__ int lane_() const { return hw_lane(); }
; __device__ __forceinline__ unsigned cvtpk(float lo, float hi) { f32x2_t v = {lo, hi}; bf16x2_t b = __builtin_convertvector(v, bf16x2_t); return __builtin_bit_cast(unsigned, b); }
; __device__ __forceinline__ float lo16(unsigned u) { return __uint_as_float(u << 16); }
; __device__ __forceinline__ float hi16(unsigned u) { return __uint_as_float(u & 0xffff0000u); }
; __device__ __forceinline__ float silu_fast(float v) { return v * __builtin_amdgcn_rcpf(1.f + __builtin_amdgcn_exp2f(-v * LOG2E)); }
; template <int NR, class Put>
; __device__ __forceinline__ void conv_compute_n(const ConvRawN<NR>& R, const float* cw, const float* cb, int col0, int rg, const Put& put) {
;     const f32x4 w0a = *(const f32x4*)(cw + col0), w0b = *(const f32x4*)(cw + col0 + 4), w1a = *(const f32x4*)(cw + XBCW + col0), w1b = *(const f32x4*)(cw + XBCW + col0 + 4);
;     const f32x4 w2a = *(const f32x4*)(cw + 2 * XBCW + col0), w2b = *(const f32x4*)(cw + 2 * XBCW + col0 + 4), ba = *(const f32x4*)(cb + col0), bb = *(const f32x4*)(cb + col0 + 4);
;     const int r0 = NR * rg;
; #pragma unroll
;     for (int rr = 0; rr < NR; ++rr) {
;         const u32x4 xm = R.r[rr], x0 = R.r[rr + 1], xp = R.r[rr + 2]; u32x4 o;
; #pragma unroll
;         for (int e = 0; e < 4; ++e) {
;             const float wl0 = e < 2 ? w0a[2 * e] : w0b[2 * e - 4], wh0 = e < 2 ? w0a[2 * e + 1] : w0b[2 * e - 3];
;             const float wl1 = e < 2 ? w1a[2 * e] : w1b[2 * e - 4], wh1 = e < 2 ? w1a[2 * e + 1] : w1b[2 * e - 3];
;             const float wl2 = e < 2 ? w2a[2 * e] : w2b[2 * e - 4], wh2 = e < 2 ? w2a[2 * e + 1] : w2b[2 * e - 3];
;             const float bl = e < 2 ? ba[2 * e] : bb[2 * e - 4], bh = e < 2 ? ba[2 * e + 1] : bb[2 * e - 3];
;             const float vl = bl + wl0 * lo16(xm[e]) + wl1 * lo16(x0[e]) + wl2 * lo16(xp[e]);
;             const float vh = bh + wh0 * hi16(xm[e]) + wh1 * hi16(x0[e]) + wh2 * hi16(xp[e]);
;             o[e] = cvtpk(silu_fast(vl), silu_fast(vh));
;         }
;         put(r0 + rr, o);
; __device__ __forceinline__ void vec_compute(Frame& F, const Ptrs& P, int b, int c, int h0, float v0, float v1, float* DEC) {
;     const int lane = F.lane_(), hl = F.wave >> 1, dir = F.wave & 1, h = h0 + hl;
;     const float A2 = -expf(dir ? P.alb[h] : P.alf[h]) * LOG2E;
	v_pk_mul_f32 v[88:89], v[108:109], v[118:119]
	v_add_f32_e32 v45, 1.0, v45
	v_cvt_pk_bf16_f32 v44, v88, v89
	v_rcp_f32_e32 v88, v45
	v_add_f32_e32 v45, 1.0, v51
	v_pk_fma_f32 v[108:109], v[60:61], v[112:113], v[64:65]
	v_rcp_f32_e32 v89, v45
	v_pk_fma_f32 v[108:109], v[68:69], v[52:53], v[108:109]
	v_lshlrev_b32_e32 v110, 16, v46
	v_and_b32_e32 v111, 0xffff0000, v46
	v_pk_fma_f32 v[108:109], v[56:57], v[110:111], v[108:109]
	v_pk_mul_f32 v[88:89], v[90:91], v[88:89]
	v_mul_f32_e32 v45, 0xbfb8aa3b, v108
	v_exp_f32_e32 v45, v45
	v_mul_f32_e32 v46, 0xbfb8aa3b, v109
	v_exp_f32_e32 v51, v46
	v_pk_fma_f32 v[90:91], v[62:63], v[94:95], v[66:67]
	v_lshlrev_b32_e32 v94, 16, v47
	v_pk_fma_f32 v[90:91], v[70:71], v[106:107], v[90:91]
	v_and_b32_e32 v95, 0xffff0000, v47
	v_pk_fma_f32 v[90:91], v[58:59], v[94:95], v[90:91]
	v_add_f32_e32 v45, 1.0, v45
	v_mul_f32_e32 v47, 0xbfb8aa3b, v90
	v_rcp_f32_e32 v46, v45
	v_add_f32_e32 v45, 1.0, v51
	v_exp_f32_e32 v51, v47
	v_mul_f32_e32 v47, 0xbfb8aa3b, v91
	v_exp_f32_e32 v55, v47
	v_rcp_f32_e32 v47, v45
	v_add_f32_e32 v45, 1.0, v51
	v_rcp_f32_e32 v112, v45
	v_add_f32_e32 v45, 1.0, v55
	v_rcp_f32_e32 v113, v45
	v_cvt_pk_bf16_f32 v45, v88, v89
	v_pk_mul_f32 v[46:47], v[108:109], v[46:47]
	v_pk_fma_f32 v[52:53], v[60:61], v[52:53], v[64:65]
	v_pk_mul_f32 v[88:89], v[90:91], v[112:113]
	v_cvt_pk_bf16_f32 v46, v46, v47
	v_cvt_pk_bf16_f32 v47, v88, v89
	v_pk_fma_f32 v[88:89], v[72:73], v[98:99], v[76:77]
	v_lshlrev_b32_e32 v90, 16, v40
	v_pk_fma_f32 v[88:89], v[80:81], v[116:117], v[88:89]
	v_and_b32_e32 v91, 0xffff0000, v40
	v_pk_fma_f32 v[88:89], v[84:85], v[90:91], v[88:89]
	ds_write_b128 v124, v[44:47] offset:64
	v_mul_f32_e32 v40, 0xbfb8aa3b, v88
	v_exp_f32_e32 v40, v40
	v_mul_f32_e32 v51, 0xbfb8aa3b, v89
	v_exp_f32_e32 v51, v51
	v_pk_fma_f32 v[46:47], v[74:75], v[48:49], v[78:79]
	v_add_f32_e32 v40, 1.0, v40
	v_rcp_f32_e32 v44, v40
	v_add_f32_e32 v40, 1.0, v51
	v_rcp_f32_e32 v45, v40
	v_pk_fma_f32 v[46:47], v[82:83], v[92:93], v[46:47]
	v_lshlrev_b32_e32 v48, 16, v41
	v_and_b32_e32 v49, 0xffff0000, v41
	v_pk_fma_f32 v[46:47], v[86:87], v[48:49], v[46:47]
	v_pk_fma_f32 v[52:53], v[68:69], v[110:111], v[52:53]
	v_mul_f32_e32 v40, 0xbfb8aa3b, v46
	v_exp_f32_e32 v51, v40
	v_mul_f32_e32 v40, 0xbfb8aa3b, v47
	v_exp_f32_e32 v55, v40
	v_pk_mul_f32 v[40:41], v[88:89], v[44:45]
	v_lshlrev_b32_e32 v88, 16, v42
	v_and_b32_e32 v89, 0xffff0000, v42
	v_pk_fma_f32 v[52:53], v[56:57], v[88:89], v[52:53]
	v_add_f32_e32 v44, 1.0, v51
	v_mul_f32_e32 v42, 0xbfb8aa3b, v52
	v_exp_f32_e32 v42, v42
	v_mul_f32_e32 v51, 0xbfb8aa3b, v53
	v_exp_f32_e32 v51, v51
	v_add_f32_e32 v45, 1.0, v55
	v_add_f32_e32 v42, 1.0, v42
	v_rcp_f32_e32 v44, v44
	v_rcp_f32_e32 v45, v45
	v_rcp_f32_e32 v98, v42
	v_add_f32_e32 v42, 1.0, v51
	v_rcp_f32_e32 v99, v42
	v_pk_mul_f32 v[44:45], v[46:47], v[44:45]
	v_pk_fma_f32 v[46:47], v[62:63], v[106:107], v[66:67]
	v_cvt_pk_bf16_f32 v40, v40, v41
	v_cvt_pk_bf16_f32 v41, v44, v45
	v_pk_mul_f32 v[44:45], v[52:53], v[98:99]
	v_pk_fma_f32 v[46:47], v[70:71], v[94:95], v[46:47]
	v_lshlrev_b32_e32 v52, 16, v43
	v_and_b32_e32 v53, 0xffff0000, v43
	v_pk_fma_f32 v[46:47], v[58:59], v[52:53], v[46:47]
	v_pk_fma_f32 v[72:73], v[72:73], v[116:117], v[76:77]
	v_mul_f32_e32 v42, 0xbfb8aa3b, v46
	v_exp_f32_e32 v43, v42
	v_mul_f32_e32 v42, 0xbfb8aa3b, v47
	v_exp_f32_e32 v51, v42
	v_lshlrev_b32_e32 v98, 16, v123
	v_and_b32_e32 v99, 0xffff0000, v123
	v_pk_fma_f32 v[72:73], v[80:81], v[90:91], v[72:73]
	v_cvt_pk_bf16_f32 v42, v44, v45
	v_pk_fma_f32 v[72:73], v[84:85], v[98:99], v[72:73]
	v_add_f32_e32 v43, 1.0, v43
	v_mul_f32_e32 v45, 0xbfb8aa3b, v72
	v_rcp_f32_e32 v44, v43
	v_add_f32_e32 v43, 1.0, v51
	v_exp_f32_e32 v51, v45
	v_mul_f32_e32 v45, 0xbfb8aa3b, v73
	v_exp_f32_e32 v55, v45
	v_rcp_f32_e32 v45, v43
	v_add_f32_e32 v43, 1.0, v51
	v_rcp_f32_e32 v76, v43
	v_add_f32_e32 v43, 1.0, v55
	v_pk_mul_f32 v[44:45], v[46:47], v[44:45]
	v_rcp_f32_e32 v77, v43
	v_cvt_pk_bf16_f32 v43, v44, v45
	v_pk_fma_f32 v[44:45], v[74:75], v[92:93], v[78:79]
	ds_write_b128 v124, v[40:43] offset:128
	v_lshlrev_b32_e32 v42, 16, v122
	v_and_b32_e32 v43, 0xffff0000, v122
	v_pk_fma_f32 v[44:45], v[82:83], v[48:49], v[44:45]
	v_pk_mul_f32 v[40:41], v[72:73], v[76:77]
	v_pk_fma_f32 v[42:43], v[86:87], v[42:43], v[44:45]
	v_pk_fma_f32 v[48:49], v[60:61], v[110:111], v[64:65]
	v_mul_f32_e32 v44, 0xbfb8aa3b, v42
	v_exp_f32_e32 v44, v44
	v_mul_f32_e32 v45, 0xbfb8aa3b, v43
	v_exp_f32_e32 v45, v45
	v_cvt_pk_bf16_f32 v40, v40, v41
	v_add_f32_e32 v41, 1.0, v44
	v_lshlrev_b32_e32 v46, 16, v121
	v_and_b32_e32 v47, 0xffff0000, v121
	v_pk_fma_f32 v[48:49], v[68:69], v[88:89], v[48:49]
	v_rcp_f32_e32 v44, v41
	v_add_f32_e32 v41, 1.0, v45
	v_pk_fma_f32 v[46:47], v[56:57], v[46:47], v[48:49]
	v_rcp_f32_e32 v45, v41
	v_mul_f32_e32 v41, 0xbfb8aa3b, v46
	v_exp_f32_e32 v41, v41
	v_mul_f32_e32 v48, 0xbfb8aa3b, v47
	v_exp_f32_e32 v48, v48
	v_pk_mul_f32 v[42:43], v[42:43], v[44:45]
	v_add_f32_e32 v41, 1.0, v41
	v_rcp_f32_e32 v44, v41
	v_add_f32_e32 v41, 1.0, v48
	v_pk_fma_f32 v[48:49], v[62:63], v[94:95], v[66:67]
	s_nop 0
	v_pk_fma_f32 v[48:49], v[70:71], v[52:53], v[48:49]
	v_lshlrev_b32_e32 v52, 16, v120
	v_and_b32_e32 v53, 0xffff0000, v120
	v_pk_fma_f32 v[48:49], v[58:59], v[52:53], v[48:49]
	s_nop 0
	v_mul_f32_e32 v45, 0xbfb8aa3b, v48
	v_exp_f32_e32 v51, v45
	v_mul_f32_e32 v45, 0xbfb8aa3b, v49
	v_exp_f32_e32 v53, v45
	v_rcp_f32_e32 v45, v41
	v_add_f32_e32 v41, 1.0, v51
	v_rcp_f32_e32 v52, v41
	v_add_f32_e32 v41, 1.0, v53
	v_rcp_f32_e32 v53, v41
	v_cvt_pk_bf16_f32 v41, v42, v43
	v_pk_mul_f32 v[42:43], v[46:47], v[44:45]
	v_pk_mul_f32 v[44:45], v[48:49], v[52:53]
	v_cvt_pk_bf16_f32 v42, v42, v43
	v_cvt_pk_bf16_f32 v43, v44, v45
	ds_write_b128 v124, v[40:43] offset:192
	v_mov_b32_e32 v40, s2
	v_mbcnt_lo_u32_b32 v41, -1, 0
	v_mbcnt_hi_u32_b32 v41, -1, v41
	v_mov_b32_e32 v40, v141
	v_cmp_gt_i32_e64 s[0:1], 32, v41
	s_waitcnt vmcnt(0)
	v_mul_f32_e32 v42, 0x3fb8aa3b, v40
	v_fma_f32 v43, v40, s78, -v42
	v_rndne_f32_e32 v44, v42
	v_fmac_f32_e32 v43, 0x32a5705f, v40
	v_sub_f32_e32 v42, v42, v44
	v_add_f32_e32 v42, v42, v43
	v_exp_f32_e32 v42, v42
	v_cvt_i32_f32_e32 v43, v44
	v_cmp_ngt_f32_e32 vcc, s79, v40
	v_ldexp_f32 v42, v42, v43
	s_nop 0
	v_cndmask_b32_e32 v42, 0, v42, vcc
	v_cmp_nlt_f32_e32 vcc, s80, v40
	s_nop 1
	v_cndmask_b32_e32 v40, v134, v42, vcc
	v_mul_f32_e32 v40, 0xbfb8aa3b, v40
	s_and_b64 vcc, exec, s[62:63]
	s_cbranch_vccz .LBB0_573
;     __device__ __forceinline__ int lane_() const { return hw_lane(); }
; __device__ __forceinline__ float shfl_from(float x, int src_lane) { return __builtin_bit_cast(float, __builtin_amdgcn_ds_bpermute(src_lane << 2, __builtin_bit_cast(int, x))); }
; __device__ __forceinline__ float incl_suffix(float x, int lane) {
; #pragma unroll
;     for (int o = 1; o < 64; o <<= 1) { const float t = shfl_from(x, lane + o < 64 ? lane + o : lane); if (lane + o < 64) x += t; }
;     return x;
; }
; __device__ __forceinline__ void vec_load(Frame& F, const Ptrs& P, int b, int c, int h0, float& v0, float& v1) {
;     const float* DT = (const float*)(P.ws + WS_DT);
;     const int lane = F.lane_(), hl = F.wave >> 1, dir = F.wave & 1, h = h0 + hl;
;     const size_t row0 = (size_t)b * SEQ + c * 128;
;     v0 = DT[(row0 + lane) * 32 + dir * 16 + h]; v1 = DT[(row0 + 64 + lane) * 32 + dir * 16 + h];
; }
; __device__ __forceinline__ void vec_compute(Frame& F, const Ptrs& P, int b, int c, int h0, float v0, float v1, float* DEC) {
;     const int lane = F.lane_(), hl = F.wave >> 1, dir = F.wave & 1, h = h0 + hl;
;     const float A2 = -expf(dir ? P.alb[h] : P.alf[h]) * LOG2E;
;     float a0, a1, aend;
;     if (dir == 0) { const float p0 = incl_prefix(v0, lane), t0 = shfl_from(p0, 63), p1 = incl_prefix(v1, lane) + t0; a0 = A2 * p0; a1 = A2 * p1; aend = shfl_from(a1, 63); }
;     else { const float s1 = incl_suffix(v1, lane), t1 = shfl_from(s1, 0), s0 = incl_suffix(v0, lane) + t1; a0 = A2 * s0; a1 = A2 * s1; aend = shfl_from(a0, 0); }
	v_cmp_gt_i32_e32 vcc, 63, v41
	v_lshlrev_b32_e32 v44, 2, v41
	v_add_u32_e32 v45, 8, v44
	v_addc_co_u32_e64 v42, s[2:3], 0, v41, vcc
	v_lshlrev_b32_e32 v42, 2, v42
	ds_bpermute_b32 v43, v42, v54
	ds_bpermute_b32 v42, v42, v50
	v_cmp_gt_i32_e64 s[2:3], 62, v41
	v_add_u32_e32 v47, 16, v44
	v_cmp_gt_i32_e64 s[4:5], 60, v41
	s_waitcnt lgkmcnt(1)
	v_add_f32_e32 v43, v54, v43
	v_cndmask_b32_e32 v43, v54, v43, vcc
	v_cndmask_b32_e64 v45, v44, v45, s[2:3]
	s_waitcnt lgkmcnt(0)
	v_add_f32_e32 v42, v50, v42
	ds_bpermute_b32 v46, v45, v43
	v_cndmask_b32_e32 v42, v50, v42, vcc
	ds_bpermute_b32 v45, v45, v42
	v_add_u32_e32 v48, 32, v44
	v_cmp_gt_i32_e64 s[6:7], 56, v41
	s_waitcnt lgkmcnt(1)
	v_add_f32_e32 v46, v43, v46
	v_cndmask_b32_e64 v43, v43, v46, s[2:3]
	v_cndmask_b32_e64 v46, v44, v47, s[4:5]
	s_waitcnt lgkmcnt(0)
	v_add_f32_e32 v45, v42, v45
	ds_bpermute_b32 v47, v46, v43
	v_cndmask_b32_e64 v42, v42, v45, s[2:3]
	ds_bpermute_b32 v45, v46, v42
	v_add_u32_e32 v46, 64, v44
	v_cmp_gt_i32_e32 vcc, 48, v41
	s_waitcnt lgkmcnt(1)
	v_add_f32_e32 v47, v43, v47
	v_cndmask_b32_e64 v43, v43, v47, s[4:5]
	v_cndmask_b32_e64 v47, v44, v48, s[6:7]
	s_waitcnt lgkmcnt(0)
	v_add_f32_e32 v45, v42, v45
	ds_bpermute_b32 v48, v47, v43
	v_cndmask_b32_e64 v42, v42, v45, s[4:5]
	ds_bpermute_b32 v45, v47, v42
	v_cndmask_b32_e32 v46, v44, v46, vcc
	s_waitcnt lgkmcnt(1)
	v_add_f32_e32 v48, v43, v48
	v_cndmask_b32_e64 v43, v43, v48, s[6:7]
	s_waitcnt lgkmcnt(0)
	v_add_f32_e32 v45, v42, v45
	ds_bpermute_b32 v48, v46, v43
	v_cndmask_b32_e64 v42, v42, v45, s[6:7]
	ds_bpermute_b32 v45, v46, v42
	v_add_u32_e32 v46, 0x80, v44
	v_cndmask_b32_e64 v44, v44, v46, s[0:1]
	s_waitcnt lgkmcnt(1)
	v_add_f32_e32 v47, v43, v48
	v_cndmask_b32_e32 v43, v43, v47, vcc
	s_waitcnt lgkmcnt(0)
	v_add_f32_e32 v45, v42, v45
	ds_bpermute_b32 v46, v44, v43
	v_cndmask_b32_e32 v45, v42, v45, vcc
	ds_bpermute_b32 v44, v44, v45
	s_waitcnt lgkmcnt(1)
	v_add_f32_e32 v42, v43, v46
	v_cndmask_b32_e64 v42, v43, v42, s[0:1]
	s_waitcnt lgkmcnt(0)
	v_add_f32_e32 v43, v45, v44
	v_readlane_b32 s2, v42, 0
	v_cndmask_b32_e64 v43, v45, v43, s[0:1]
	s_nop 0
	v_add_f32_e32 v43, s2, v43
	v_pk_mul_f32 v[42:43], v[40:41], v[42:43] op_sel_hi:[0,1]
	s_nop 0
	v_readlane_b32 s2, v43, 0
	s_cbranch_execz .LBB0_574
	s_branch .LBB0_575
